# v030
# speedup vs baseline: 1.0153x; 1.0021x over previous
.LBB0_298:
	s_or_b64 exec, exec, s[8:9]
	v_mov_b32_e32 v0, s51
	s_waitcnt lgkmcnt(0)
	s_barrier
	ds_read_b32 v0, v0
	s_waitcnt lgkmcnt(0)
	v_cmp_gt_i32_e32 vcc, 0, v0
	v_readfirstlane_b32 s2, v0
	s_cbranch_vccnz .LBB0_340
	s_mul_hi_u32 s3, s2, 0xaaaaaaab
	s_lshr_b32 s3, s3, 8
	s_mul_i32 s5, s3, 0x180
	s_sub_i32 s5, s2, s5
	s_lshr_b32 s7, s5, 2
	s_and_b32 s7, s7, 0x78
	s_sub_i32 s8, s7, s3
	s_and_b32 s2, s5, 32
	s_add_i32 s8, s8, 7
	s_add_i32 s7, s7, s3
	s_cmp_eq_u32 s2, 0
	s_cselect_b32 s3, s7, s8
	s_mul_hi_i32 s7, s3, 0x2aaaaaab
	s_lshr_b32 s8, s7, 31
	s_mul_hi_i32 s21, s3, 0xd5555555
	s_add_i32 s7, s7, s8
	s_lshr_b32 s2, s21, 31
	s_mul_i32 s7, s7, 6
	s_add_i32 s21, s21, s2
	s_sub_i32 s3, s3, s7
	s_add_i32 s2, s21, 15
	s_and_b32 s5, s5, 31
	s_lshl_b32 s7, s3, 5
	s_cmp_lt_i32 s3, 4
	s_cselect_b32 s7, s7, 0
	s_lshl_b32 s8, s2, 4
	s_add_i32 s8, s8, 0
	s_add_i32 s8, s8, 0x20000
	v_mov_b32_e32 v0, s8
	s_max_i32 s3, s3, 3
	s_waitcnt vmcnt(0)
	ds_read_b96 v[2:4], v0
	s_or_b32 s22, s5, s7
	s_add_i32 s18, s3, -3
	s_cmp_eq_u32 s18, 1
	s_movk_i32 s3, 0x5000
	v_readfirstlane_b32 s9, v195
	s_cselect_b32 s25, 0x4000, s3
	s_bfe_u32 s5, s9, 0x20006
	s_lshl_b32 s10, s22, 7
	s_lshl_b32 s11, s5, 5
	s_lshr_b32 s3, s9, 6
	s_lshr_b32 s7, s9, 8
	s_or_b32 s23, s11, s10
	s_mul_i32 s12, s2, 0x600000
	s_waitcnt lgkmcnt(0)
	v_readfirstlane_b32 s8, v2
	s_mul_hi_i32 s11, s2, 0x600000
	s_add_u32 s16, s63, s12
	s_addc_u32 s17, s4, s11
	s_sub_i32 s11, s10, s8
	s_or_b32 s24, s10, 0x7f
	s_ashr_i32 s11, s11, 6
	s_add_i32 s8, s8, s24
	s_lshl_b32 s80, s7, 7
	s_add_i32 s33, s21, 16
	s_max_i32 s11, s11, 0
	s_ashr_i32 s12, s8, 6
	s_cmpk_lt_u32 s9, 0x100
	s_cselect_b64 s[8:9], -1, 0
	s_and_b64 s[14:15], s[8:9], exec
	v_readfirstlane_b32 s13, v3
	v_readfirstlane_b32 s19, v4
	s_cselect_b32 s14, 16, 32
	v_mov_b32_e32 v0, v195
	v_mov_b32_e32 v181, v194
	s_cselect_b32 s13, s13, s19
	s_add_i32 s15, s14, s2
	s_lshl_b32 s19, s5, 11
	s_cmp_eq_u32 s18, 0
	v_and_b32_e32 v0, 31, v181
	s_cselect_b32 s14, 0, s25
	v_or_b32_e32 v10, s23, v0
	v_add_u32_e32 v164, s14, v10
	v_ashrrev_i32_e32 v165, 31, v164
	v_ashrrev_i32_e32 v186, 5, v181
	v_lshlrev_b64 v[2:3], 8, v[164:165]
	v_lshl_add_u64 v[2:3], s[16:17], 0, v[2:3]
	v_lshlrev_b32_e32 v166, 3, v186
	v_lshl_add_u64 v[2:3], v[2:3], 0, s[80:81]
	v_ashrrev_i32_e32 v167, 31, v166
	v_lshl_add_u64 v[2:3], v[166:167], 1, v[2:3]
	global_load_dwordx4 v[144:147], v[2:3], off
	global_load_dwordx4 v[148:151], v[2:3], off offset:32
	global_load_dwordx4 v[152:155], v[2:3], off offset:64
	global_load_dwordx4 v[156:159], v[2:3], off offset:96
	v_lshlrev_b32_e32 v3, 2, v181
	v_lshl_add_u32 v2, s7, 3, v186
	v_and_b32_e32 v3, 12, v3
	v_bfe_u32 v4, v181, 2, 2
	v_lshlrev_b32_e32 v0, 8, v0
	v_bitop3_b32 v5, v3, v2, v4 bitop3:0x36
	v_lshl_add_u32 v182, v5, 4, v0
	v_add_u32_e32 v5, 2, v2
	v_bitop3_b32 v5, v3, v5, v4 bitop3:0x36
	v_lshl_add_u32 v183, v5, 4, v0
	v_add_u32_e32 v5, 4, v2
	v_add_u32_e32 v2, 6, v2
	v_bitop3_b32 v5, v3, v5, v4 bitop3:0x36
	v_bitop3_b32 v2, v3, v2, v4 bitop3:0x36
	v_lshl_add_u32 v184, v5, 4, v0
	v_lshl_add_u32 v185, v2, 4, v0
	v_ashrrev_i32_e32 v0, 4, v181
	v_lshlrev_b32_e32 v3, 1, v0
	v_and_b32_e32 v7, 12, v181
	v_lshlrev_b32_e32 v11, 2, v186
	v_and_b32_e32 v3, 2, v3
	v_bfe_u32 v5, v181, 1, 1
	v_lshlrev_b32_e32 v8, 3, v181
	v_and_or_b32 v9, v186, 3, v7
	v_or_b32_e32 v6, v3, v5
	v_and_b32_e32 v12, 8, v8
	v_or_b32_e32 v8, v11, v4
	v_bitop3_b32 v3, v3, v9, v5 bitop3:0x36
	v_lshlrev_b32_e32 v8, 8, v8
	v_lshlrev_b32_e32 v3, 4, v3
	v_or3_b32 v187, v3, v8, v12
	v_add_u32_e32 v3, 8, v11
	v_or_b32_e32 v4, v3, v4
	v_bfe_u32 v3, v3, 2, 2
	v_lshlrev_b32_e32 v13, 8, v4
	v_bitop3_b32 v4, v3, v6, v7 bitop3:0x36
	v_lshlrev_b32_e32 v4, 4, v4
	v_or3_b32 v188, v4, v13, v12
	v_or_b32_e32 v4, 4, v6
	v_bitop3_b32 v4, v3, v4, v7 bitop3:0x36
	v_bitop3_b32 v5, v6, v9, 4 bitop3:0x36
	v_lshlrev_b32_e32 v4, 4, v4
	v_lshlrev_b32_e32 v5, 4, v5
	v_or3_b32 v190, v4, v13, v12
	v_or_b32_e32 v4, 8, v6
	v_or3_b32 v189, v5, v8, v12
	v_bitop3_b32 v5, v6, v9, 8 bitop3:0x36
	v_bitop3_b32 v4, v3, v4, v7 bitop3:0x36
	v_lshlrev_b32_e32 v5, 4, v5
	v_lshlrev_b32_e32 v4, 4, v4
	v_or3_b32 v191, v5, v8, v12
	v_or3_b32 v192, v4, v13, v12
	v_or_b32_e32 v4, 12, v6
	v_bitop3_b32 v5, v6, v9, 12 bitop3:0x36
	v_cvt_f32_i32_e32 v6, s33
	v_and_b32_e32 v2, 15, v181
	v_bitop3_b32 v14, v3, v4, v7 bitop3:0x36
	v_lshlrev_b32_e32 v5, 4, v5
	v_mul_f32_e32 v3, -0.5, v6
	v_exp_f32_e32 v15, v3
	v_lshl_add_u32 v3, v0, 7, s19
	v_lshlrev_b32_e32 v0, 5, v0
	v_lshlrev_b32_e32 v2, 3, v2
	v_or3_b32 v193, v5, v8, v12
	v_xor_b32_e32 v5, v0, v2
	v_xor_b32_e32 v2, 8, v5
	s_movk_i32 s17, 0x200
	v_add3_u32 v2, v3, v2, s17
	v_xor_b32_e32 v4, 16, v5
	s_movk_i32 s17, 0x400
	v_add_u32_e32 v0, v3, v5
	v_add3_u32 v4, v3, v4, s17
	v_xor_b32_e32 v5, 24, v5
	s_movk_i32 s17, 0x600
	v_add3_u32 v6, v3, v5, s17
	s_mul_hi_i32 s16, s15, 0x600000
	s_mul_i32 s15, s15, 0x600000
	s_waitcnt vmcnt(2)
	v_and_b32_e32 v7, 0xffff0000, v148
	v_and_b32_e32 v5, 0xffff0000, v144
	v_lshlrev_b32_e32 v3, 16, v144
	v_mul_f32_e32 v5, v5, v5
	v_fmac_f32_e32 v5, v3, v3
	v_lshlrev_b32_e32 v3, 16, v145
	v_fmac_f32_e32 v5, v3, v3
	v_and_b32_e32 v3, 0xffff0000, v145
	v_fmac_f32_e32 v5, v3, v3
	v_lshlrev_b32_e32 v3, 16, v146
	v_fmac_f32_e32 v5, v3, v3
	v_and_b32_e32 v3, 0xffff0000, v146
	v_fmac_f32_e32 v5, v3, v3
	v_lshlrev_b32_e32 v3, 16, v147
	v_fmac_f32_e32 v5, v3, v3
	v_and_b32_e32 v3, 0xffff0000, v147
	v_fmac_f32_e32 v5, v3, v3
	v_lshlrev_b32_e32 v3, 16, v148
	v_mul_f32_e32 v7, v7, v7
	v_fmac_f32_e32 v7, v3, v3
	v_lshlrev_b32_e32 v3, 16, v149
	v_fmac_f32_e32 v7, v3, v3
	v_and_b32_e32 v3, 0xffff0000, v149
	v_fmac_f32_e32 v7, v3, v3
	v_lshlrev_b32_e32 v3, 16, v150
	v_fmac_f32_e32 v7, v3, v3
	v_and_b32_e32 v3, 0xffff0000, v150
	v_fmac_f32_e32 v7, v3, v3
	v_lshlrev_b32_e32 v3, 16, v151
	v_fmac_f32_e32 v7, v3, v3
	v_and_b32_e32 v3, 0xffff0000, v151
	v_fmac_f32_e32 v7, v3, v3
	v_add_f32_e32 v3, v5, v7
	s_waitcnt vmcnt(1)
	v_and_b32_e32 v7, 0xffff0000, v152
	v_lshlrev_b32_e32 v5, 16, v152
	v_mul_f32_e32 v7, v7, v7
	v_fmac_f32_e32 v7, v5, v5
	v_lshlrev_b32_e32 v5, 16, v153
	v_fmac_f32_e32 v7, v5, v5
	v_and_b32_e32 v5, 0xffff0000, v153
	v_fmac_f32_e32 v7, v5, v5
	v_lshlrev_b32_e32 v5, 16, v154
	v_fmac_f32_e32 v7, v5, v5
	v_and_b32_e32 v5, 0xffff0000, v154
	s_cselect_b32 s17, 0xff, 63
	s_add_u32 s15, s63, s15
	v_fmac_f32_e32 v7, v5, v5
	v_lshlrev_b32_e32 v5, 16, v155
	s_addc_u32 s16, s4, s16
	s_lshl_b32 s14, s14, 8
	v_fmac_f32_e32 v7, v5, v5
	v_and_b32_e32 v5, 0xffff0000, v155
	s_add_u32 s33, s15, s14
	v_fmac_f32_e32 v7, v5, v5
	s_waitcnt vmcnt(0)
	v_and_b32_e32 v5, 0xffff0000, v156
	s_addc_u32 s37, s16, 0
	s_lshr_b32 s44, s11, 1
	s_ashr_i32 s11, s10, 31
	v_add_f32_e32 v16, v3, v7
	v_lshlrev_b32_e32 v3, 16, v156
	v_mul_f32_e32 v17, v5, v5
	s_lshl_b64 s[14:15], s[10:11], 8
	v_fmac_f32_e32 v17, v3, v3
	v_lshlrev_b32_e32 v3, 16, v157
	s_add_u32 s14, s33, s14
	v_fmac_f32_e32 v17, v3, v3
	v_and_b32_e32 v3, 0xffff0000, v157
	s_addc_u32 s15, s37, s15
	s_lshl_b32 s11, s7, 14
	v_fmac_f32_e32 v17, v3, v3
	v_lshlrev_b32_e32 v3, 16, v158
	s_add_i32 s45, s11, 0
	s_lshl_b32 s11, s5, 12
	v_fmac_f32_e32 v17, v3, v3
	s_add_i32 s45, s45, s11
	v_lshlrev_b64 v[168:169], 1, v[0:1]
	v_mov_b32_e32 v3, v1
	v_lshl_add_u64 v[8:9], s[14:15], 0, v[168:169]
	s_mov_b32 m0, s45
	v_lshlrev_b64 v[170:171], 1, v[2:3]
	v_mov_b32_e32 v5, v1
	global_load_lds_dwordx4 v[8:9], off
	v_lshl_add_u64 v[2:3], s[14:15], 0, v[170:171]
	s_add_i32 m0, s45, 0x400
	v_lshlrev_b64 v[172:173], 1, v[4:5]
	global_load_lds_dwordx4 v[2:3], off
	v_lshl_add_u64 v[2:3], s[14:15], 0, v[172:173]
	s_add_i32 m0, s45, 0x800
	v_mov_b32_e32 v7, v1
	global_load_lds_dwordx4 v[2:3], off
	v_lshlrev_b64 v[174:175], 1, v[6:7]
	s_add_i32 m0, s45, 0xc00
	v_lshl_add_u64 v[2:3], s[14:15], 0, v[174:175]
	s_add_u32 s14, s14, 0x4000
	s_addc_u32 s15, s15, 0
	global_load_lds_dwordx4 v[2:3], off
	s_add_i32 m0, s45, 0x8000
	v_lshl_add_u64 v[2:3], s[14:15], 0, v[168:169]
	global_load_lds_dwordx4 v[2:3], off
	v_lshl_add_u64 v[2:3], s[14:15], 0, v[170:171]
	s_add_i32 m0, s45, 0x8400
	v_and_b32_e32 v0, 0xffff0000, v158
	global_load_lds_dwordx4 v[2:3], off
	v_lshl_add_u64 v[2:3], s[14:15], 0, v[172:173]
	s_add_i32 m0, s45, 0x8800
	v_fmac_f32_e32 v17, v0, v0
	global_load_lds_dwordx4 v[2:3], off
	v_lshl_add_u64 v[2:3], s[14:15], 0, v[174:175]
	s_add_i32 m0, s45, 0x8c00
	v_lshlrev_b32_e32 v0, 16, v159
	global_load_lds_dwordx4 v[2:3], off
	v_fmac_f32_e32 v17, v0, v0
	v_and_b32_e32 v0, 0xffff0000, v159
	v_fmac_f32_e32 v17, v0, v0
	v_add_f32_e32 v0, v16, v17
	v_mov_b32_e32 v2, v0
	s_nop 1
	v_permlane32_swap_b32_e32 v0, v2
	v_add_f32_e32 v0, v0, v2
	v_mul_f32_e32 v2, 0x4f800000, v0
	v_cmp_gt_f32_e32 vcc, s65, v0
	v_lshlrev_b32_e32 v3, 4, v14
	v_or3_b32 v196, v3, v13, v12
	v_cndmask_b32_e32 v0, v0, v2, vcc
	v_sqrt_f32_e32 v2, v0
	s_min_i32 s11, s17, s12
	s_ashr_i32 s46, s11, 1
	s_lshl_b32 s11, s3, 2
	v_add_u32_e32 v3, -1, v2
	v_fma_f32 v4, -v3, v2, v0
	v_cmp_ge_f32_e64 s[38:39], 0, v4
	v_add_u32_e32 v4, 1, v2
	s_add_i32 s48, s11, 0
	v_cndmask_b32_e64 v3, v2, v3, s[38:39]
	v_fma_f32 v2, -v4, v2, v0
	v_cmp_lt_f32_e64 s[38:39], 0, v2
	s_or_b32 s47, s23, 31
	s_add_i32 s48, s48, 0x20440
	v_cndmask_b32_e64 v2, v3, v4, s[38:39]
	v_mul_f32_e32 v3, 0x37800000, v2
	v_cndmask_b32_e32 v2, v2, v3, vcc
	v_cmp_class_f32_e32 vcc, v0, v227
	s_add_i32 s49, s22, 1
	s_cmp_lt_i32 s22, s46
	v_cndmask_b32_e32 v0, v2, v0, vcc
	v_mul_f32_e32 v176, 0x3fb8aa3b, v15
	v_mul_f32_e32 v0, 0x3e3a82f9, v0
	s_cselect_b32 s11, s49, -1
	s_add_i32 s12, s22, -1
	s_or_b32 s50, s10, 1
	v_mov_b32_e32 v14, v1
	v_mov_b32_e32 v15, v1
	v_mul_f32_e32 v197, s13, v0
	v_sub_u32_e32 v198, v11, v10
	v_xor_b32_e32 v178, 0x80000000, v176
	s_cmp_gt_i32 s22, s44
	v_mov_b32_e32 v0, v1
	v_mov_b32_e32 v2, v1
	v_mov_b32_e32 v3, v1
	v_mov_b32_e32 v4, v1
	v_mov_b32_e32 v6, v1
	v_mov_b32_e32 v8, v1
	v_mov_b32_e32 v9, v1
	v_mov_b32_e32 v10, v1
	v_mov_b32_e32 v11, v1
	v_mov_b32_e32 v12, v1
	v_mov_b32_e32 v13, v1
	v_mov_b64_e32 v[30:31], v[14:15]
	v_mov_b64_e32 v[46:47], v[14:15]
	v_mov_b64_e32 v[62:63], v[14:15]
	v_mov_b64_e32 v[78:79], v[14:15]
	s_mov_b32 s25, 0
	v_cmp_eq_u32_e64 s[38:39], 0, v181
	s_cselect_b32 s79, s12, s11
	s_cselect_b32 s78, 1, 2
	v_mov_b32_e32 v177, v176
	v_mov_b32_e32 v179, v178
	v_mul_f32_e32 v201, 0xc27c0000, v176
	v_add_f32_e32 v201, 0x41000000, v201
	s_nop 0
	v_readfirstlane_b32 s100, v201
	v_mov_b32_e32 v201, 0
	v_mov_b32_e32 v199, 0
	s_mov_b32 s83, 0
	v_mov_b32_e32 v180, 0
	v_mov_b64_e32 v[28:29], v[12:13]
	v_mov_b64_e32 v[26:27], v[10:11]
	v_mov_b64_e32 v[24:25], v[8:9]
	v_mov_b64_e32 v[22:23], v[6:7]
	v_mov_b64_e32 v[20:21], v[4:5]
	v_mov_b64_e32 v[18:19], v[2:3]
	v_mov_b64_e32 v[16:17], v[0:1]
	v_mov_b64_e32 v[44:45], v[12:13]
	v_mov_b64_e32 v[42:43], v[10:11]
	v_mov_b64_e32 v[40:41], v[8:9]
	v_mov_b64_e32 v[38:39], v[6:7]
	v_mov_b64_e32 v[36:37], v[4:5]
	v_mov_b64_e32 v[34:35], v[2:3]
	v_mov_b64_e32 v[32:33], v[0:1]
	v_mov_b64_e32 v[60:61], v[12:13]
	v_mov_b64_e32 v[58:59], v[10:11]
	v_mov_b64_e32 v[56:57], v[8:9]
	v_mov_b64_e32 v[54:55], v[6:7]
	v_mov_b64_e32 v[52:53], v[4:5]
	v_mov_b64_e32 v[50:51], v[2:3]
	v_mov_b64_e32 v[48:49], v[0:1]
	v_mov_b64_e32 v[76:77], v[12:13]
	v_mov_b64_e32 v[74:75], v[10:11]
	v_mov_b64_e32 v[72:73], v[8:9]
	v_mov_b64_e32 v[70:71], v[6:7]
	v_mov_b64_e32 v[68:69], v[4:5]
	v_mov_b64_e32 v[66:67], v[2:3]
	v_mov_b64_e32 v[64:65], v[0:1]
	s_mov_b32 s18, s22
	s_mov_b32 s10, 0
	v_readfirstlane_b32 s101, v195
	s_cmpk_lt_u32 s101, 0x100
	s_cbranch_scc1 .Lmy_prio_lo
	s_setprio 1

.LBB0_308:
	s_andn2_b64 vcc, exec, s[16:17]
	s_cbranch_vccnz .LBB0_310
	s_lshl_b32 s80, s51, 7
	s_lshl_b64 s[16:17], s[80:81], 8
	s_add_u32 s16, s33, s16
	s_addc_u32 s17, s37, s17
	s_and_b32 s19, s25, 0x10000
	s_xor_b32 s40, s19, 0x10000
	s_add_i32 s40, s45, s40
	s_cmpk_lt_u32 s101, 0x100
	s_cbranch_scc1 .LBB0_310
	s_mov_b32 m0, s40
	s_nop 0
	global_load_lds_dwordx4 v168, s[16:17]
	s_add_i32 m0, s40, 0x400
	s_nop 0
	global_load_lds_dwordx4 v170, s[16:17]
	s_add_i32 m0, s40, 0x800
	s_nop 0
	global_load_lds_dwordx4 v172, s[16:17]
	s_add_i32 m0, s40, 0xc00
	s_nop 0
	global_load_lds_dwordx4 v174, s[16:17]
	s_add_u32 s16, s16, 0x4000
	s_addc_u32 s17, s17, 0
	s_add_i32 m0, s40, 0x8000
	s_nop 0
	global_load_lds_dwordx4 v168, s[16:17]
	s_add_i32 m0, s40, 0x8400
	s_nop 0
	global_load_lds_dwordx4 v170, s[16:17]
	s_add_i32 m0, s40, 0x8800
	s_nop 0
	global_load_lds_dwordx4 v172, s[16:17]
	s_add_i32 m0, s40, 0x8c00
	s_nop 0
	global_load_lds_dwordx4 v174, s[16:17]
	s_sub_u32 s16, s16, 0x6004000
	s_subb_u32 s17, s17, 0
	s_add_i32 s40, s40, 0xffffc000
	s_mov_b32 m0, s40
	s_nop 0
	global_load_lds_dwordx4 v168, s[16:17]
	s_add_i32 m0, s40, 0x400
	s_nop 0
	global_load_lds_dwordx4 v170, s[16:17]
	s_add_i32 m0, s40, 0x800
	s_nop 0
	global_load_lds_dwordx4 v172, s[16:17]
	s_add_i32 m0, s40, 0xc00
	s_nop 0
	global_load_lds_dwordx4 v174, s[16:17]
	s_add_u32 s16, s16, 0x4000
	s_addc_u32 s17, s17, 0
	s_add_i32 m0, s40, 0x8000
	s_nop 0
	global_load_lds_dwordx4 v168, s[16:17]
	s_add_i32 m0, s40, 0x8400
	s_nop 0
	global_load_lds_dwordx4 v170, s[16:17]
	s_add_i32 m0, s40, 0x8800
	s_nop 0
	global_load_lds_dwordx4 v172, s[16:17]
	s_add_i32 m0, s40, 0x8c00
	s_nop 0
	global_load_lds_dwordx4 v174, s[16:17]
.LBB0_310:
	s_add_i32 s40, s19, 0
	v_add_u32_e32 v210, s40, v182
	ds_read_b128 v[2:5], v210
	ds_read_b128 v[6:9], v210 offset:8192
	v_add_u32_e32 v208, s40, v183
	ds_read_b128 v[10:13], v208
	v_add_u32_e32 v209, s40, v184
	ds_read_b128 v[80:83], v209
	s_lshl_b32 s80, s18, 7
	v_add_u32_e32 v211, s40, v185
	v_add_u32_e32 v0, s80, v198
	s_waitcnt lgkmcnt(0)
	v_mfma_f32_32x32x16_bf16 v[112:127], v[2:5], v[144:147], 0
	ds_read_b128 v[2:5], v208 offset:8192
	s_or_b32 s16, s80, 63
	v_cvt_f32_i32_e32 v0, v0
	s_cmp_ge_i32 s16, s23
	s_cselect_b64 s[16:17], -1, 0
	s_cmp_le_i32 s80, s47
	s_cselect_b64 s[18:19], -1, 0
	v_mfma_f32_32x32x16_bf16 v[112:127], v[10:13], v[148:151], v[112:127]
	ds_read_b128 v[10:13], v209 offset:8192
	ds_read_b128 v[84:87], v211
	ds_read_b128 v[88:91], v211 offset:8192
	v_mfma_f32_32x32x16_bf16 v[112:127], v[80:83], v[152:155], v[112:127]
	v_mfma_f32_32x32x16_bf16 v[128:143], v[6:9], v[144:147], 0
	v_add_u32_e32 v14, s40, v187
	v_add_u32_e32 v204, s40, v191
	v_add_u32_e32 v15, s40, v188
	v_add_u32_e32 v202, s40, v189
	v_add_u32_e32 v203, s40, v190
	ds_read_b64_tr_b16 v[160:161], v14 offset:16384
	ds_read_b64_tr_b16 v[162:163], v15 offset:16384
	ds_read_b64_tr_b16 v[6:7], v202 offset:16384
	ds_read_b64_tr_b16 v[8:9], v203 offset:16384
	v_add_u32_e32 v205, s40, v192
	s_waitcnt lgkmcnt(7)
	v_mfma_f32_32x32x16_bf16 v[128:143], v[2:5], v[148:151], v[128:143]
	v_add_u32_e32 v206, s40, v193
	v_add_u32_e32 v207, s40, v196
	s_waitcnt lgkmcnt(6)
	v_mfma_f32_32x32x16_bf16 v[128:143], v[10:13], v[152:155], v[128:143]
	ds_read_b64_tr_b16 v[10:11], v204 offset:16384
	ds_read_b64_tr_b16 v[12:13], v205 offset:16384
	ds_read_b64_tr_b16 v[2:3], v206 offset:16384
	ds_read_b64_tr_b16 v[4:5], v207 offset:16384
	s_waitcnt lgkmcnt(8)
	v_mfma_f32_32x32x16_bf16 v[128:143], v[88:91], v[156:159], v[128:143]
	v_mfma_f32_32x32x16_bf16 v[112:127], v[84:87], v[156:159], v[112:127]
	s_and_b64 s[18:19], s[16:17], s[18:19]
	s_andn2_b64 vcc, exec, s[18:19]
	s_mov_b64 s[18:19], -1
	s_cbranch_vccz .LBB0_312
	v_cndmask_b32_e64 v94, v176, -v176, s[16:17]
	v_fma_f32 v212, v94, v0, -v180
	v_add_f32_e32 v213, v197, v212
	s_andn2_b64 vcc, exec, s[14:15]
	s_cbranch_vccnz .Lmy_slow0
	s_cmp_eq_u64 s[16:17], 0
	s_cselect_b32 s54, s100, s70
	v_cmp_lt_f32_e32 vcc, s54, v213
	s_cbranch_vccnz .Lmy_slow0
	v_add_f32_e32 v81, v94, v212
	v_fma_f32 v96, v112, s62, v212
	v_fma_f32 v97, v113, s62, v81
	v_fma_f32 v80, v94, s76, v212
	v_fma_f32 v81, v94, s77, v212
	v_fma_f32 v98, v114, s62, v80
	v_fma_f32 v99, v115, s62, v81
	v_fma_f32 v80, v94, s70, v212
	v_fma_f32 v81, v94, s71, v212
	v_fma_f32 v100, v116, s62, v80
	v_fma_f32 v101, v117, s62, v81
	v_fma_f32 v80, v94, s74, v212
	v_fma_f32 v81, v94, s75, v212
	v_fma_f32 v102, v118, s62, v80
	v_fma_f32 v103, v119, s62, v81
	v_fma_f32 v80, v94, s28, v212
	v_fma_f32 v81, v94, s29, v212
	v_fma_f32 v104, v120, s62, v80
	v_fma_f32 v105, v121, s62, v81
	v_fma_f32 v80, v94, s26, v212
	v_fma_f32 v81, v94, s27, v212
	v_fma_f32 v106, v122, s62, v80
	v_fma_f32 v107, v123, s62, v81
	v_fma_f32 v80, v94, s86, v212
	v_fma_f32 v81, v94, s87, v212
	v_fma_f32 v108, v124, s62, v80
	v_fma_f32 v109, v125, s62, v81
	v_fma_f32 v80, v94, s72, v212
	v_fma_f32 v81, v94, s73, v212
	v_fma_f32 v110, v126, s62, v80
	v_fma_f32 v111, v127, s62, v81
	v_fma_f32 v80, v94, s68, v212
	v_fma_f32 v81, v94, s69, v212
	v_fma_f32 v80, v128, s62, v80
	v_fma_f32 v81, v129, s62, v81
	v_fma_f32 v82, v94, s60, v212
	v_fma_f32 v83, v94, s61, v212
	v_fma_f32 v82, v130, s62, v82
	v_fma_f32 v83, v131, s62, v83
	v_fma_f32 v84, v94, s34, v212
	v_fma_f32 v85, v94, s35, v212
	v_fma_f32 v84, v132, s62, v84
	v_fma_f32 v85, v133, s62, v85
	v_fma_f32 v86, v94, s88, v212
	v_fma_f32 v87, v94, s89, v212
	v_fma_f32 v86, v134, s62, v86
	v_fma_f32 v87, v135, s62, v87
	v_fma_f32 v88, v94, s90, v212
	v_fma_f32 v89, v94, s91, v212
	v_fma_f32 v88, v136, s62, v88
	v_fma_f32 v89, v137, s62, v89
	v_fma_f32 v90, v94, s92, v212
	v_fma_f32 v91, v94, s93, v212
	v_fma_f32 v90, v138, s62, v90
	v_fma_f32 v91, v139, s62, v91
	v_fma_f32 v92, v94, s94, v212
	v_fma_f32 v93, v94, s95, v212
	v_fma_f32 v92, v140, s62, v92
	v_fma_f32 v93, v141, s62, v93
	v_fma_f32 v95, v94, s97, v212
	v_fma_f32 v94, v94, s96, v212
	v_fma_f32 v94, v142, s62, v94
	v_fma_f32 v95, v143, s62, v95
	s_branch .LBB0_321

.LBB0_321:
	v_exp_f32_e32 v212, v96
	v_exp_f32_e32 v213, v97
	v_exp_f32_e32 v214, v98
	v_exp_f32_e32 v215, v99
	v_exp_f32_e32 v216, v100
	v_exp_f32_e32 v217, v101
	v_exp_f32_e32 v218, v102
	v_exp_f32_e32 v219, v103
	v_cvt_pk_bf16_f32 v96, v212, v213
	v_cvt_pk_bf16_f32 v97, v214, v215
	v_cvt_pk_bf16_f32 v98, v216, v217
	v_cvt_pk_bf16_f32 v99, v218, v219
	s_waitcnt lgkmcnt(4)
	s_nop 0
	v_mfma_f32_32x32x16_bf16 v[48:63], v[6:9], v[96:99], v[48:63]
	s_waitcnt lgkmcnt(2)
	v_mfma_f32_32x32x16_bf16 v[32:47], v[10:13], v[96:99], v[32:47]
	ds_read_b64_tr_b16 v[6:7], v14 offset:20480
	ds_read_b64_tr_b16 v[8:9], v15 offset:20480
	ds_read_b64_tr_b16 v[10:11], v202 offset:20480
	ds_read_b64_tr_b16 v[12:13], v203 offset:20480
	ds_read_b64_tr_b16 v[100:101], v204 offset:20480
	ds_read_b64_tr_b16 v[102:103], v205 offset:20480
	ds_read_b64_tr_b16 v[112:113], v206 offset:20480
	ds_read_b64_tr_b16 v[114:115], v207 offset:20480
	v_mfma_f32_32x32x16_bf16 v[64:79], v[160:163], v[96:99], v[64:79]
	s_waitcnt lgkmcnt(8)
	v_mfma_f32_32x32x16_bf16 v[16:31], v[2:5], v[96:99], v[16:31]
	v_exp_f32_e32 v220, v104
	v_exp_f32_e32 v221, v105
	v_exp_f32_e32 v222, v106
	v_exp_f32_e32 v223, v107
	v_exp_f32_e32 v224, v108
	v_exp_f32_e32 v225, v109
	v_exp_f32_e32 v228, v110
	v_exp_f32_e32 v246, v111
	v_cvt_pk_bf16_f32 v2, v220, v221
	v_cvt_pk_bf16_f32 v3, v222, v223
	v_cvt_pk_bf16_f32 v4, v224, v225
	v_cvt_pk_bf16_f32 v5, v228, v246
	s_waitcnt lgkmcnt(6)
	s_nop 0
	v_mfma_f32_32x32x16_bf16 v[64:79], v[6:9], v[2:5], v[64:79]
	s_waitcnt lgkmcnt(4)
	v_mfma_f32_32x32x16_bf16 v[48:63], v[10:13], v[2:5], v[48:63]
	s_waitcnt lgkmcnt(2)
	v_mfma_f32_32x32x16_bf16 v[32:47], v[100:103], v[2:5], v[32:47]
	ds_read_b64_tr_b16 v[6:7], v14 offset:24576
	ds_read_b64_tr_b16 v[8:9], v15 offset:24576
	ds_read_b64_tr_b16 v[10:11], v202 offset:24576
	ds_read_b64_tr_b16 v[12:13], v203 offset:24576
	ds_read_b64_tr_b16 v[96:97], v204 offset:24576
	ds_read_b64_tr_b16 v[98:99], v205 offset:24576
	ds_read_b64_tr_b16 v[100:101], v206 offset:24576
	ds_read_b64_tr_b16 v[102:103], v207 offset:24576
	s_waitcnt lgkmcnt(8)
	v_mfma_f32_32x32x16_bf16 v[16:31], v[112:115], v[2:5], v[16:31]
	v_exp_f32_e32 v247, v80
	v_exp_f32_e32 v248, v81
	v_exp_f32_e32 v249, v82
	v_exp_f32_e32 v250, v83
	v_exp_f32_e32 v251, v84
	v_exp_f32_e32 v252, v85
	v_exp_f32_e32 v231, v86
	v_exp_f32_e32 v232, v87
	v_cvt_pk_bf16_f32 v2, v247, v248
	v_cvt_pk_bf16_f32 v3, v249, v250
	v_cvt_pk_bf16_f32 v4, v251, v252
	v_cvt_pk_bf16_f32 v5, v231, v232
	s_waitcnt lgkmcnt(6)
	s_nop 0
	v_mfma_f32_32x32x16_bf16 v[64:79], v[6:9], v[2:5], v[64:79]
	s_waitcnt lgkmcnt(4)
	v_mfma_f32_32x32x16_bf16 v[48:63], v[10:13], v[2:5], v[48:63]
	ds_read_b64_tr_b16 v[6:7], v14 offset:28672
	ds_read_b64_tr_b16 v[8:9], v15 offset:28672
	ds_read_b64_tr_b16 v[10:11], v202 offset:28672
	ds_read_b64_tr_b16 v[12:13], v203 offset:28672
	ds_read_b64_tr_b16 v[80:81], v204 offset:28672
	ds_read_b64_tr_b16 v[82:83], v205 offset:28672
	ds_read_b64_tr_b16 v[84:85], v206 offset:28672
	ds_read_b64_tr_b16 v[86:87], v207 offset:28672
	s_waitcnt lgkmcnt(10)
	v_mfma_f32_32x32x16_bf16 v[32:47], v[96:99], v[2:5], v[32:47]
	s_waitcnt lgkmcnt(8)
	v_mfma_f32_32x32x16_bf16 v[16:31], v[100:103], v[2:5], v[16:31]
	v_exp_f32_e32 v233, v88
	v_exp_f32_e32 v234, v89
	v_exp_f32_e32 v235, v90
	v_exp_f32_e32 v236, v91
	v_exp_f32_e32 v237, v92
	v_exp_f32_e32 v238, v93
	v_exp_f32_e32 v239, v94
	v_exp_f32_e32 v240, v95
	v_cvt_pk_bf16_f32 v2, v233, v234
	v_cvt_pk_bf16_f32 v3, v235, v236
	v_cvt_pk_bf16_f32 v4, v237, v238
	v_cvt_pk_bf16_f32 v5, v239, v240
	s_waitcnt lgkmcnt(6)
	s_nop 0
	v_mfma_f32_32x32x16_bf16 v[64:79], v[6:9], v[2:5], v[64:79]
	s_waitcnt lgkmcnt(4)
	v_mfma_f32_32x32x16_bf16 v[48:63], v[10:13], v[2:5], v[48:63]
	s_waitcnt lgkmcnt(2)
	v_mfma_f32_32x32x16_bf16 v[32:47], v[80:83], v[2:5], v[32:47]
	s_waitcnt lgkmcnt(0)
	v_mfma_f32_32x32x16_bf16 v[16:31], v[84:87], v[2:5], v[16:31]
	ds_read_b128 v[2:5], v210 offset:32768
	ds_read_b128 v[6:9], v210 offset:40960
	s_or_b32 s18, s80, 64
	v_add_u32_e32 v0, s18, v198
	s_or_b32 s14, s80, 0x7f
	s_waitcnt lgkmcnt(1)
	v_mfma_f32_32x32x16_bf16 v[112:127], v[2:5], v[144:147], 0
	ds_read_b128 v[2:5], v208 offset:32768
	ds_read_b128 v[10:13], v208 offset:40960
	ds_read_b128 v[80:83], v209 offset:32768
	v_cvt_f32_i32_e32 v0, v0
	s_cmp_ge_i32 s14, s23
	s_cselect_b64 s[14:15], -1, 0
	s_cmp_le_i32 s18, s47
	s_cselect_b64 s[16:17], -1, 0
	s_waitcnt lgkmcnt(2)
	v_mfma_f32_32x32x16_bf16 v[112:127], v[2:5], v[148:151], v[112:127]
	ds_read_b128 v[2:5], v209 offset:40960
	ds_read_b128 v[84:87], v211 offset:32768
	ds_read_b128 v[88:91], v211 offset:40960
	s_waitcnt lgkmcnt(3)
	v_mfma_f32_32x32x16_bf16 v[112:127], v[80:83], v[152:155], v[112:127]
	v_mfma_f32_32x32x16_bf16 v[128:143], v[6:9], v[144:147], 0
	v_mfma_f32_32x32x16_bf16 v[128:143], v[10:13], v[148:151], v[128:143]
	s_waitcnt lgkmcnt(2)
	v_mfma_f32_32x32x16_bf16 v[128:143], v[2:5], v[152:155], v[128:143]
	ds_read_b64_tr_b16 v[160:161], v14 offset:49152
	ds_read_b64_tr_b16 v[162:163], v15 offset:49152
	ds_read_b64_tr_b16 v[10:11], v202 offset:49152
	ds_read_b64_tr_b16 v[12:13], v203 offset:49152
	ds_read_b64_tr_b16 v[6:7], v204 offset:49152
	ds_read_b64_tr_b16 v[8:9], v205 offset:49152
	ds_read_b64_tr_b16 v[2:3], v206 offset:49152
	ds_read_b64_tr_b16 v[4:5], v207 offset:49152
	s_waitcnt lgkmcnt(8)
	v_mfma_f32_32x32x16_bf16 v[128:143], v[88:91], v[156:159], v[128:143]
	v_mfma_f32_32x32x16_bf16 v[112:127], v[84:87], v[156:159], v[112:127]
	s_and_b64 s[18:19], s[14:15], s[16:17]
	s_mov_b64 s[16:17], -1
	s_and_b64 vcc, exec, s[18:19]
	s_cbranch_vccnz .LBB0_323
	v_cndmask_b32_e64 v94, v176, -v176, s[14:15]
	v_fma_f32 v208, v94, v0, -v180
	v_add_f32_e32 v209, v197, v208
	s_cmp_eq_u64 s[14:15], 0
	s_cselect_b32 s54, s100, s70
	v_cmp_lt_f32_e32 vcc, s54, v209
	s_cbranch_vccnz .Lmy_slow1
	v_add_f32_e32 v81, v94, v208
	s_nop 1
	v_fma_f32 v96, v112, s62, v208
	v_fma_f32 v97, v113, s62, v81
	v_fma_f32 v80, v94, s76, v208
	v_fma_f32 v81, v94, s77, v208
	v_fma_f32 v98, v114, s62, v80
	v_fma_f32 v99, v115, s62, v81
	v_fma_f32 v80, v94, s70, v208
	v_fma_f32 v81, v94, s71, v208
	v_fma_f32 v100, v116, s62, v80
	v_fma_f32 v101, v117, s62, v81
	v_fma_f32 v80, v94, s74, v208
	v_fma_f32 v81, v94, s75, v208
	v_fma_f32 v102, v118, s62, v80
	v_fma_f32 v103, v119, s62, v81
	v_fma_f32 v80, v94, s28, v208
	v_fma_f32 v81, v94, s29, v208
	v_fma_f32 v104, v120, s62, v80
	v_fma_f32 v105, v121, s62, v81
	v_fma_f32 v80, v94, s26, v208
	v_fma_f32 v81, v94, s27, v208
	v_fma_f32 v106, v122, s62, v80
	v_fma_f32 v107, v123, s62, v81
	v_fma_f32 v80, v94, s86, v208
	v_fma_f32 v81, v94, s87, v208
	v_fma_f32 v108, v124, s62, v80
	v_fma_f32 v109, v125, s62, v81
	v_fma_f32 v80, v94, s72, v208
	v_fma_f32 v81, v94, s73, v208
	v_fma_f32 v110, v126, s62, v80
	v_fma_f32 v111, v127, s62, v81
	v_fma_f32 v80, v94, s68, v208
	v_fma_f32 v81, v94, s69, v208
	v_fma_f32 v80, v128, s62, v80
	v_fma_f32 v81, v129, s62, v81
	v_fma_f32 v82, v94, s60, v208
	v_fma_f32 v83, v94, s61, v208
	v_fma_f32 v82, v130, s62, v82
	v_fma_f32 v83, v131, s62, v83
	v_fma_f32 v84, v94, s34, v208
	v_fma_f32 v85, v94, s35, v208
	v_fma_f32 v84, v132, s62, v84
	v_fma_f32 v85, v133, s62, v85
	v_fma_f32 v86, v94, s88, v208
	v_fma_f32 v87, v94, s89, v208
	v_fma_f32 v86, v134, s62, v86
	v_fma_f32 v87, v135, s62, v87
	v_fma_f32 v88, v94, s90, v208
	v_fma_f32 v89, v94, s91, v208
	v_fma_f32 v88, v136, s62, v88
	v_fma_f32 v89, v137, s62, v89
	v_fma_f32 v90, v94, s92, v208
	v_fma_f32 v91, v94, s93, v208
	v_fma_f32 v90, v138, s62, v90
	v_fma_f32 v91, v139, s62, v91
	v_fma_f32 v92, v94, s94, v208
	v_fma_f32 v93, v94, s95, v208
	v_fma_f32 v92, v140, s62, v92
	v_fma_f32 v93, v141, s62, v93
	v_fma_f32 v95, v94, s97, v208
	v_fma_f32 v94, v94, s96, v208
	v_fma_f32 v94, v142, s62, v94
	v_fma_f32 v95, v143, s62, v95
	s_branch .Lmy_fast1_sum
